# S5 full tile: lane^1 exchange of the new state via DPP quad_perm instead of four ds_bpermute round trips (and the index arithmetic that fed them)
# speedup vs baseline: 1.0037x; 1.0037x over previous
.LBB0_919:
	s_cmp_lt_u32 s36, s101
	s_cbranch_scc1 .Ls5_state_only
	ds_read_b128 v[174:177], v166
	ds_read_b128 v[178:181], v166 offset:64
	ds_read_b128 v[182:185], v166 offset:128
	ds_read_b128 v[186:189], v166 offset:192
	s_and_b32 s38, s37, 1
	s_waitcnt lgkmcnt(3)
	v_mfma_f32_16x16x32_bf16 v[64:67], v[174:177], v[20:23], v[64:67]
	s_xor_b32 s39, s38, 1
	s_mulk_i32 s39, 0x1100
	s_waitcnt lgkmcnt(1)
	v_mfma_f32_16x16x32_bf16 v[190:193], v[182:185], v[28:31], 0
	v_mfma_f32_16x16x32_bf16 v[64:67], v[178:181], v[24:27], v[64:67]
	s_waitcnt lgkmcnt(0)
	v_mfma_f32_16x16x32_bf16 v[190:193], v[186:189], v[32:35], v[190:193]
	s_nop 7
	v_pk_add_f32 v[200:201], v[64:65], v[190:191]
	v_add_u32_e32 v64, s39, v117
	v_pk_add_f32 v[198:199], v[66:67], v[192:193]
	v_cvt_pk_bf16_f32 v65, v200, s0
	v_add_u32_e32 v66, v64, v124
	ds_write_b16 v66, v65 offset:59392
	v_cvt_pk_bf16_f32 v65, v201, s0
	v_add_u32_e32 v64, v64, v125
	ds_write_b16 v64, v65 offset:59392
	v_cvt_pk_bf16_f32 v65, v198, s0
	ds_write_b16 v64, v65 offset:59664
	v_cvt_pk_bf16_f32 v65, v199, s0
	ds_write_b16 v64, v65 offset:59936
	s_mulk_i32 s38, 0x1100
	v_add_u32_e32 v167, s38, v118
	v_mfma_f32_16x16x32_bf16 v[64:67], v[174:177], v[44:47], 0
	ds_read_b128 v[174:177], v167 offset:59392
	v_mfma_f32_16x16x32_bf16 v[64:67], v[178:181], v[40:43], v[64:67]
	ds_read_b128 v[178:181], v167 offset:59456
	ds_read_b128 v[190:193], v167 offset:59520
	ds_read_b128 v[194:197], v167 offset:59584
	v_mfma_f32_16x16x32_bf16 v[64:67], v[182:185], v[36:39], v[64:67]
	s_add_i32 s37, s37, 1
	v_add_u32_e32 v166, 0x1100, v166
	s_waitcnt lgkmcnt(3)
	v_mfma_f32_16x16x32_bf16 v[174:177], v[174:177], v[4:7], 0
	s_waitcnt lgkmcnt(2)
	v_mfma_f32_16x16x32_bf16 v[174:177], v[178:181], v[8:11], v[174:177]
	v_mov_b32_dpp v182, v200 quad_perm:[1,0,3,2] row_mask:0xf bank_mask:0xf
	v_mov_b32_dpp v184, v198 quad_perm:[1,0,3,2] row_mask:0xf bank_mask:0xf
	v_mov_b32_dpp v185, v199 quad_perm:[1,0,3,2] row_mask:0xf bank_mask:0xf
	s_waitcnt lgkmcnt(1)
	v_mfma_f32_16x16x32_bf16 v[174:177], v[190:193], v[12:15], v[174:177]
	v_mov_b32_dpp v183, v201 quad_perm:[1,0,3,2] row_mask:0xf bank_mask:0xf
	s_waitcnt lgkmcnt(0)
	v_pk_mul_f32 v[184:185], v[80:81], v[184:185]
	v_mfma_f32_16x16x32_bf16 v[174:177], v[194:197], v[16:19], v[174:177]
	s_waitcnt lgkmcnt(0)
	v_pk_mul_f32 v[182:183], v[68:69], v[182:183]
	v_mfma_f32_16x16x32_bf16 v[64:67], v[186:189], v[0:3], v[64:67]
	s_nop 7
	v_add_f32_e32 v64, v174, v64
	v_mul_f32_e32 v167, 0x3d372713, v64
	v_mul_f32_e32 v167, v64, v167
	v_fma_f32 v167, v64, v167, v64
	v_add_f32_e32 v169, v175, v65
	v_mul_f32_e32 v65, 0xbfcc422a, v167
	v_mul_f32_e32 v167, 0x3d372713, v169
	v_mul_f32_e32 v167, v169, v167
	v_mul_f32_e32 v65, 0x3fb8aa3b, v65
	v_fma_f32 v167, v169, v167, v169
	v_exp_f32_e32 v65, v65
	v_mul_f32_e32 v167, 0xbfcc422a, v167
	v_mul_f32_e32 v167, 0x3fb8aa3b, v167
	v_exp_f32_e32 v167, v167
	v_add_f32_e32 v66, v176, v66
	v_mul_f32_e32 v175, 0x3d372713, v66
	v_add_f32_e32 v65, 1.0, v65
	v_mul_f32_e32 v175, v66, v175
	v_rcp_f32_e32 v65, v65
	v_fma_f32 v175, v66, v175, v66
	v_add_f32_e32 v167, 1.0, v167
	v_mul_f32_e32 v175, 0xbfcc422a, v175
	v_rcp_f32_e32 v167, v167
	v_mul_f32_e32 v175, 0x3fb8aa3b, v175
	v_exp_f32_e32 v175, v175
	v_mul_f32_e32 v64, v64, v65
	v_cvt_pk_bf16_f32 v174, v64, s0
	v_lshl_add_u64 v[64:65], v[88:89], 0, s[2:3]
	global_store_short v[64:65], v174, off
	v_mul_f32_e32 v64, v169, v167
	v_cvt_pk_bf16_f32 v167, v64, s0
	v_add_f32_e32 v64, 1.0, v175
	v_add_f32_e32 v67, v177, v67
	v_rcp_f32_e32 v169, v64
	v_mul_f32_e32 v64, 0x3d372713, v67
	v_mul_f32_e32 v64, v67, v64
	v_fma_f32 v64, v67, v64, v67
	v_mul_f32_e32 v64, 0xbfcc422a, v64
	v_mul_f32_e32 v64, 0x3fb8aa3b, v64
	v_exp_f32_e32 v174, v64
	v_lshl_add_u64 v[64:65], v[86:87], 0, s[2:3]
	global_store_short v[64:65], v167, off
	v_mul_f32_e32 v64, v66, v169
	v_add_f32_e32 v65, 1.0, v174
	v_rcp_f32_e32 v66, v65
	v_cvt_pk_bf16_f32 v167, v64, s0
	v_lshl_add_u64 v[64:65], v[84:85], 0, s[2:3]
	global_store_short v[64:65], v167, off
	v_mul_f32_e32 v64, v67, v66
	v_cvt_pk_bf16_f32 v66, v64, s0
	v_lshl_add_u64 v[64:65], v[82:83], 0, s[2:3]
	s_add_u32 s2, s2, 0x4000
	s_addc_u32 s3, s3, 0
	global_store_short v[64:65], v66, off
	v_pk_fma_f32 v[66:67], v[78:79], v[198:199], v[184:185]
	v_pk_fma_f32 v[64:65], v[100:101], v[200:201], v[182:183]
	s_cmp_eq_u32 s2, 0x10000
	s_cbranch_scc1 .LBB0_917
